# scan waves: the last step of a trip issues its operand loads before the first product so they land before the barrier
# baseline (speedup 1.0000x reference)
; __device__ __forceinline__ void phase_scan(const Params& p, LAS unsigned char* lds) {
;     ...
;                     const LAS float* sR = OPS + (n & 1) * SET_F + j0; const LAS float* sW = sR + 2048; const LAS float* sK = sW + 2048; const LAS float* sA = sK + 2048; const LAS float* sB = sA + 2048; const LAS float* sV = OPS + (n & 1) * SET_F + 10240;
;                     LAS float* sY = sYb + (n & 1) * 512;
;                     f32x4 a_ = *(const LAS f32x4*)(sA), w_ = *(const LAS f32x4*)(sW), b_ = *(const LAS f32x4*)(sB);
;                     f32x4 k_ = *(const LAS f32x4*)(sK), r_ = *(const LAS f32x4*)(sR);
;                     f32x4 vq[4];
; #pragma unroll
;                     for (int u = 0; u < 4; ++u) vq[u] = *(const LAS f32x4*)(sV + srow * 32 + 4 * u);
;                     f32x4 rp = r_;
; #pragma unroll
;                     for (int hb = 0; hb < 2; ++hb) {
;                         f32x4 vn[4];
; #pragma unroll
;                         for (int u = 0; u < 4; ++u) vn[u] = *(const LAS f32x4*)(sV + srow * 32 + ((16 * (hb + 1)) & 31) + 4 * u);
; #pragma unroll
;                         for (int u16 = 0; u16 < 16; ++u16) {
;                             const int s = 16 * hb + u16;
;                             const int sn = (s + 1) & 31;
;                             const f32x4 a_n = *(const LAS f32x4*)(sA + sn * 64), w_n = *(const LAS f32x4*)(sW + sn * 64), b_n = *(const LAS f32x4*)(sB + sn * 64);
;                             const f32x4 k_n = *(const LAS f32x4*)(sK + sn * 64), r_n = *(const LAS f32x4*)(sR + sn * 64);
;                             const float v = vq[u16 >> 2][u16 & 3];
;                             const f32x2 vv = {v, v};
;                             f32x2 pp = S01 * (f32x2){a_[0], a_[1]}; pp = S23 * (f32x2){a_[2], a_[3]} + pp;
;                             f32x2 yy = S01 * (f32x2){rp[0], rp[1]}; yy = S23 * (f32x2){rp[2], rp[3]} + yy;
;                             float sa = pp[0] + pp[1], y = yy[0] + yy[1];
;                             sa += dpp_f<0xB1>(sa); y += dpp_f<0xB1>(y);
;                             sa += dpp_f<0x4E>(sa); y += dpp_f<0x4E>(y);
;                             sa += dpp_f<0x141>(sa); y += dpp_f<0x141>(y);
;                             sa += dpp_f<0x140>(sa); y += dpp_f<0x140>(y);
;                             sY[((s - 1) & 31) * 16 + srow] = y;
;                             const f32x2 sv = {sa, sa};
.Lscan_trip:
	s_and_b32 s14, s81, 1
	s_mul_i32 s15, s14, 0xa800
	s_add_i32 s15, s15, 0x8800
	v_add_u32_e32 v124, s15, v178
	v_add_u32_e32 v125, s15, v179
	s_cmp_eq_u32 s81, 0
	s_cselect_b32 s14, 0xc000c000, -1
	s_mov_b32 s15, s14
	v_pk_mul_f32 v[114:115], v[166:167], v[22:23]
	v_pk_mul_f32 v[116:117], v[166:167], v[18:19]
	v_pk_fma_f32 v[114:115], v[164:165], v[24:25], v[114:115]
	v_pk_fma_f32 v[116:117], v[164:165], v[20:21], v[116:117]
	v_add_f32_e32 v122, v114, v115
	v_pk_mul_f32 v[118:119], v[110:111], v[34:35] op_sel:[1,0]
	v_add_f32_e32 v214, v116, v117
	ds_read_b128 v[14:17], v124 offset:16384
	ds_read_b128 v[6:9], v124 offset:8192
	ds_read_b128 v[10:13], v124 offset:32768
	ds_read_b128 v[18:21], v124 offset:0
	ds_read_b128 v[2:5], v124 offset:24576
	ds_read_b128 v[82:85], v125 offset:40960
	v_add_f32_dpp v122, v122, v122 quad_perm:[1,0,3,2] row_mask:0xf bank_mask:0xf bound_ctrl:1
	v_pk_mul_f32 v[120:121], v[110:111], v[36:37] op_sel:[1,0]
	v_add_f32_dpp v204, v204, v204 row_mirror row_mask:0xf bank_mask:0xf bound_ctrl:1
	v_add_f32_dpp v122, v122, v122 quad_perm:[2,3,0,1] row_mask:0xf bank_mask:0xf bound_ctrl:1
	v_pk_fma_f32 v[166:167], v[166:167], v[26:27], v[118:119]
	v_add_f32_dpp v204, v212, v212 row_mirror row_mask:0xf bank_mask:0xc bound_ctrl:1
	v_add_f32_dpp v122, v122, v122 row_half_mirror row_mask:0xf bank_mask:0xf bound_ctrl:1
	v_pk_fma_f32 v[164:165], v[164:165], v[28:29], v[120:121]
	v_add_f32_dpp v205, v205, v205 row_mirror row_mask:0xf bank_mask:0xf bound_ctrl:1
	v_add_f32_dpp v122, v122, v122 row_mirror row_mask:0xf bank_mask:0xf bound_ctrl:1
	v_add_f32_dpp v205, v213, v213 row_mirror row_mask:0xf bank_mask:0xc bound_ctrl:1
	v_add_f32_dpp v206, v206, v206 row_mirror row_mask:0xf bank_mask:0xf bound_ctrl:1
	v_pk_fma_f32 v[166:167], v[30:31], v[122:123], v[166:167] op_sel_hi:[1,0,1]
	v_pk_fma_f32 v[164:165], v[32:33], v[122:123], v[164:165] op_sel_hi:[1,0,1]
	v_add_f32_dpp v206, v214, v214 row_mirror row_mask:0xf bank_mask:0xc bound_ctrl:1
	v_pk_mul_f32 v[114:115], v[166:167], v[42:43]
	v_pk_mul_f32 v[116:117], v[166:167], v[38:39]
	v_pk_fma_f32 v[114:115], v[164:165], v[44:45], v[114:115]
	v_pk_fma_f32 v[116:117], v[164:165], v[40:41], v[116:117]
	v_add_f32_e32 v122, v114, v115
	v_pk_mul_f32 v[118:119], v[112:113], v[54:55] op_sel_hi:[0,1]
	v_add_f32_e32 v215, v116, v117
	ds_read_b128 v[34:37], v124 offset:16640
	ds_read_b128 v[26:29], v124 offset:8448
	ds_read_b128 v[30:33], v124 offset:33024
	ds_read_b128 v[38:41], v124 offset:256
	ds_read_b128 v[22:25], v124 offset:24832
	v_add_f32_dpp v122, v122, v122 quad_perm:[1,0,3,2] row_mask:0xf bank_mask:0xf bound_ctrl:1
	v_pk_mul_f32 v[120:121], v[112:113], v[56:57] op_sel_hi:[0,1]
	v_add_f32_dpp v207, v207, v207 row_mirror row_mask:0xf bank_mask:0xf bound_ctrl:1
	v_add_f32_dpp v122, v122, v122 quad_perm:[2,3,0,1] row_mask:0xf bank_mask:0xf bound_ctrl:1
	v_pk_fma_f32 v[166:167], v[166:167], v[46:47], v[118:119]
	v_add_f32_dpp v207, v215, v215 row_mirror row_mask:0xf bank_mask:0xc bound_ctrl:1
	v_add_f32_dpp v122, v122, v122 row_half_mirror row_mask:0xf bank_mask:0xf bound_ctrl:1
	v_pk_fma_f32 v[164:165], v[164:165], v[48:49], v[120:121]
	s_nop 0
	v_add_f32_dpp v122, v122, v122 row_mirror row_mask:0xf bank_mask:0xf bound_ctrl:1
	s_nop 0
	v_pk_fma_f32 v[166:167], v[50:51], v[122:123], v[166:167] op_sel_hi:[1,0,1]
	v_pk_fma_f32 v[164:165], v[52:53], v[122:123], v[164:165] op_sel_hi:[1,0,1]
	v_pk_mul_f32 v[114:115], v[166:167], v[62:63]
	v_pk_mul_f32 v[116:117], v[166:167], v[58:59]
	v_pk_fma_f32 v[114:115], v[164:165], v[64:65], v[114:115]
	v_pk_fma_f32 v[116:117], v[164:165], v[60:61], v[116:117]
	v_add_f32_e32 v122, v114, v115
	v_pk_mul_f32 v[118:119], v[112:113], v[74:75] op_sel:[1,0]
	v_add_f32_e32 v216, v116, v117
	ds_read_b128 v[54:57], v124 offset:16896
	ds_read_b128 v[46:49], v124 offset:8704
	ds_read_b128 v[50:53], v124 offset:33280
	ds_read_b128 v[58:61], v124 offset:512
	ds_read_b128 v[42:45], v124 offset:25088
	v_add_f32_dpp v122, v122, v122 quad_perm:[1,0,3,2] row_mask:0xf bank_mask:0xf bound_ctrl:1
	v_pk_mul_f32 v[120:121], v[112:113], v[76:77] op_sel:[1,0]
	v_add_f32_dpp v208, v208, v208 row_mirror row_mask:0xf bank_mask:0xf bound_ctrl:1
	v_add_f32_dpp v122, v122, v122 quad_perm:[2,3,0,1] row_mask:0xf bank_mask:0xf bound_ctrl:1
	v_pk_fma_f32 v[166:167], v[166:167], v[66:67], v[118:119]
	v_add_f32_dpp v208, v216, v216 row_mirror row_mask:0xf bank_mask:0xc bound_ctrl:1
	v_add_f32_dpp v122, v122, v122 row_half_mirror row_mask:0xf bank_mask:0xf bound_ctrl:1
	v_pk_fma_f32 v[164:165], v[164:165], v[68:69], v[120:121]
	s_nop 0
	v_add_f32_dpp v122, v122, v122 row_mirror row_mask:0xf bank_mask:0xf bound_ctrl:1
	s_nop 0
	v_pk_fma_f32 v[166:167], v[70:71], v[122:123], v[166:167] op_sel_hi:[1,0,1]
	v_pk_fma_f32 v[164:165], v[72:73], v[122:123], v[164:165] op_sel_hi:[1,0,1]
	s_waitcnt lgkmcnt(11)
	v_pk_mul_f32 v[114:115], v[166:167], v[2:3]
	v_pk_mul_f32 v[116:117], v[166:167], v[78:79]
	v_pk_fma_f32 v[114:115], v[164:165], v[4:5], v[114:115]
	v_pk_fma_f32 v[116:117], v[164:165], v[80:81], v[116:117]
	v_add_f32_e32 v122, v114, v115
	s_waitcnt lgkmcnt(10)
; #define LAS __attribute__((address_space(3)))
; template <int CTRL> __device__ __forceinline__ float dpp_f(float x) { return __int_as_float(__builtin_amdgcn_update_dpp(0, __float_as_int(x), CTRL, 0xf, 0xf, false)); }
; __device__ __forceinline__ void phase_scan(const Params& p, LAS unsigned char* lds) {
;     ...
;                         for (int u16 = 0; u16 < 16; ++u16) {
;                             const int s = 16 * hb + u16;
;                             const int sn = (s + 1) & 31;
;                             const f32x4 a_n = *(const LAS f32x4*)(sA + sn * 64), w_n = *(const LAS f32x4*)(sW + sn * 64), b_n = *(const LAS f32x4*)(sB + sn * 64);
;                             const f32x4 k_n = *(const LAS f32x4*)(sK + sn * 64), r_n = *(const LAS f32x4*)(sR + sn * 64);
;                             const float v = vq[u16 >> 2][u16 & 3];
;                             const f32x2 vv = {v, v};
;                             f32x2 pp = S01 * (f32x2){a_[0], a_[1]}; pp = S23 * (f32x2){a_[2], a_[3]} + pp;
;                             f32x2 yy = S01 * (f32x2){rp[0], rp[1]}; yy = S23 * (f32x2){rp[2], rp[3]} + yy;
;                             float sa = pp[0] + pp[1], y = yy[0] + yy[1];
;                             sa += dpp_f<0xB1>(sa); y += dpp_f<0xB1>(y);
;                             sa += dpp_f<0x4E>(sa); y += dpp_f<0x4E>(y);
;                             sa += dpp_f<0x141>(sa); y += dpp_f<0x141>(y);
;                             sa += dpp_f<0x140>(sa); y += dpp_f<0x140>(y);
;                             sY[((s - 1) & 31) * 16 + srow] = y;
;                             const f32x2 sv = {sa, sa};
;                             S01 = S01 * (f32x2){w_[0], w_[1]} + vv * (f32x2){k_[0], k_[1]};
;                             S23 = S23 * (f32x2){w_[2], w_[3]} + vv * (f32x2){k_[2], k_[3]};
;                             S01 = sv * (f32x2){b_[0], b_[1]} + S01;
;                             S23 = sv * (f32x2){b_[2], b_[3]} + S23;
;                             rp = r_;
;                             a_ = a_n; w_ = w_n; b_ = b_n; k_ = k_n; r_ = r_n;
;                         }
	v_pk_mul_f32 v[118:119], v[82:83], v[14:15] op_sel_hi:[0,1]
	v_add_f32_e32 v217, v116, v117
	ds_read_b128 v[74:77], v124 offset:17152
	ds_read_b128 v[66:69], v124 offset:8960
	ds_read_b128 v[70:73], v124 offset:33536
	ds_read_b128 v[78:81], v124 offset:768
	ds_read_b128 v[62:65], v124 offset:25344
	v_add_f32_dpp v122, v122, v122 quad_perm:[1,0,3,2] row_mask:0xf bank_mask:0xf bound_ctrl:1
	v_pk_mul_f32 v[120:121], v[82:83], v[16:17] op_sel_hi:[0,1]
	v_add_f32_dpp v209, v209, v209 row_mirror row_mask:0xf bank_mask:0xf bound_ctrl:1
	v_add_f32_dpp v122, v122, v122 quad_perm:[2,3,0,1] row_mask:0xf bank_mask:0xf bound_ctrl:1
	v_pk_fma_f32 v[166:167], v[166:167], v[6:7], v[118:119]
	v_add_f32_dpp v209, v217, v217 row_mirror row_mask:0xf bank_mask:0xc bound_ctrl:1
	v_add_f32_dpp v122, v122, v122 row_half_mirror row_mask:0xf bank_mask:0xf bound_ctrl:1
	v_pk_fma_f32 v[164:165], v[164:165], v[8:9], v[120:121]
	s_nop 0
	v_add_f32_dpp v122, v122, v122 row_mirror row_mask:0xf bank_mask:0xf bound_ctrl:1
	s_nop 0
	v_pk_fma_f32 v[166:167], v[10:11], v[122:123], v[166:167] op_sel_hi:[1,0,1]
	v_pk_fma_f32 v[164:165], v[12:13], v[122:123], v[164:165] op_sel_hi:[1,0,1]
	s_waitcnt lgkmcnt(10)
	v_pk_mul_f32 v[114:115], v[166:167], v[22:23]
	v_pk_mul_f32 v[116:117], v[166:167], v[18:19]
	v_pk_fma_f32 v[114:115], v[164:165], v[24:25], v[114:115]
	v_pk_fma_f32 v[116:117], v[164:165], v[20:21], v[116:117]
	v_add_f32_e32 v122, v114, v115
	v_pk_mul_f32 v[118:119], v[82:83], v[34:35] op_sel:[1,0]
	v_add_f32_e32 v218, v116, v117
	ds_read_b128 v[14:17], v124 offset:17408
	ds_read_b128 v[6:9], v124 offset:9216
	ds_read_b128 v[10:13], v124 offset:33792
	ds_read_b128 v[18:21], v124 offset:1024
	ds_read_b128 v[2:5], v124 offset:25600
	ds_read_b128 v[86:89], v125 offset:40976
	v_add_f32_dpp v122, v122, v122 quad_perm:[1,0,3,2] row_mask:0xf bank_mask:0xf bound_ctrl:1
	v_pk_mul_f32 v[120:121], v[82:83], v[36:37] op_sel:[1,0]
	v_add_f32_dpp v210, v210, v210 row_mirror row_mask:0xf bank_mask:0xf bound_ctrl:1
	v_add_f32_dpp v122, v122, v122 quad_perm:[2,3,0,1] row_mask:0xf bank_mask:0xf bound_ctrl:1
	v_pk_fma_f32 v[166:167], v[166:167], v[26:27], v[118:119]
	v_add_f32_dpp v210, v218, v218 row_mirror row_mask:0xf bank_mask:0xc bound_ctrl:1
	v_add_f32_dpp v122, v122, v122 row_half_mirror row_mask:0xf bank_mask:0xf bound_ctrl:1
	v_pk_fma_f32 v[164:165], v[164:165], v[28:29], v[120:121]
	s_nop 0
	v_add_f32_dpp v122, v122, v122 row_mirror row_mask:0xf bank_mask:0xf bound_ctrl:1
	s_nop 0
	v_pk_fma_f32 v[166:167], v[30:31], v[122:123], v[166:167] op_sel_hi:[1,0,1]
	v_pk_fma_f32 v[164:165], v[32:33], v[122:123], v[164:165] op_sel_hi:[1,0,1]
	s_waitcnt lgkmcnt(11)
	v_pk_mul_f32 v[114:115], v[166:167], v[42:43]
	v_pk_mul_f32 v[116:117], v[166:167], v[38:39]
	v_pk_fma_f32 v[114:115], v[164:165], v[44:45], v[114:115]
	v_pk_fma_f32 v[116:117], v[164:165], v[40:41], v[116:117]
	v_add_f32_e32 v122, v114, v115
	v_pk_mul_f32 v[118:119], v[84:85], v[54:55] op_sel_hi:[0,1]
	v_add_f32_e32 v219, v116, v117
	ds_read_b128 v[34:37], v124 offset:17664
	ds_read_b128 v[26:29], v124 offset:9472
	ds_read_b128 v[30:33], v124 offset:34048
	ds_read_b128 v[38:41], v124 offset:1280
	ds_read_b128 v[22:25], v124 offset:25856
	v_add_f32_dpp v122, v122, v122 quad_perm:[1,0,3,2] row_mask:0xf bank_mask:0xf bound_ctrl:1
	v_pk_mul_f32 v[120:121], v[84:85], v[56:57] op_sel_hi:[0,1]
	v_add_f32_dpp v211, v211, v211 row_mirror row_mask:0xf bank_mask:0xf bound_ctrl:1
	v_add_f32_dpp v122, v122, v122 quad_perm:[2,3,0,1] row_mask:0xf bank_mask:0xf bound_ctrl:1
	v_pk_fma_f32 v[166:167], v[166:167], v[46:47], v[118:119]
	v_add_f32_dpp v211, v219, v219 row_mirror row_mask:0xf bank_mask:0xc bound_ctrl:1
	v_add_f32_dpp v122, v122, v122 row_half_mirror row_mask:0xf bank_mask:0xf bound_ctrl:1
	v_pk_fma_f32 v[164:165], v[164:165], v[48:49], v[120:121]
	v_add_f32_dpp v204, v204, v204 row_half_mirror row_mask:0xf bank_mask:0xf bound_ctrl:1
	v_add_f32_dpp v122, v122, v122 row_mirror row_mask:0xf bank_mask:0xf bound_ctrl:1
	v_add_f32_dpp v205, v205, v205 row_half_mirror row_mask:0xf bank_mask:0xf bound_ctrl:1
	v_add_f32_dpp v206, v206, v206 row_half_mirror row_mask:0xf bank_mask:0xf bound_ctrl:1
	v_pk_fma_f32 v[166:167], v[50:51], v[122:123], v[166:167] op_sel_hi:[1,0,1]
	v_pk_fma_f32 v[164:165], v[52:53], v[122:123], v[164:165] op_sel_hi:[1,0,1]
	v_add_f32_dpp v207, v207, v207 row_half_mirror row_mask:0xf bank_mask:0xf bound_ctrl:1
	v_add_f32_dpp v204, v208, v208 row_half_mirror row_mask:0xf bank_mask:0xa bound_ctrl:1
	s_waitcnt lgkmcnt(11)
	v_pk_mul_f32 v[114:115], v[166:167], v[62:63]
	v_pk_mul_f32 v[116:117], v[166:167], v[58:59]
	v_pk_fma_f32 v[114:115], v[164:165], v[64:65], v[114:115]
	v_pk_fma_f32 v[116:117], v[164:165], v[60:61], v[116:117]
	v_add_f32_e32 v122, v114, v115
	v_pk_mul_f32 v[118:119], v[84:85], v[74:75] op_sel:[1,0]
	v_add_f32_e32 v220, v116, v117
	ds_read_b128 v[54:57], v124 offset:17920
	ds_read_b128 v[46:49], v124 offset:9728
	ds_read_b128 v[50:53], v124 offset:34304
	ds_read_b128 v[58:61], v124 offset:1536
	ds_read_b128 v[42:45], v124 offset:26112
	v_add_f32_dpp v122, v122, v122 quad_perm:[1,0,3,2] row_mask:0xf bank_mask:0xf bound_ctrl:1
	v_pk_mul_f32 v[120:121], v[84:85], v[76:77] op_sel:[1,0]
	v_add_f32_dpp v205, v209, v209 row_half_mirror row_mask:0xf bank_mask:0xa bound_ctrl:1
	v_add_f32_dpp v122, v122, v122 quad_perm:[2,3,0,1] row_mask:0xf bank_mask:0xf bound_ctrl:1
	v_pk_fma_f32 v[166:167], v[166:167], v[66:67], v[118:119]
	v_add_f32_dpp v206, v210, v210 row_half_mirror row_mask:0xf bank_mask:0xa bound_ctrl:1
	v_add_f32_dpp v122, v122, v122 row_half_mirror row_mask:0xf bank_mask:0xf bound_ctrl:1
	v_pk_fma_f32 v[164:165], v[164:165], v[68:69], v[120:121]
	v_add_f32_dpp v207, v211, v211 row_half_mirror row_mask:0xf bank_mask:0xa bound_ctrl:1
	v_add_f32_dpp v122, v122, v122 row_mirror row_mask:0xf bank_mask:0xf bound_ctrl:1
	v_add_f32_dpp v204, v204, v204 quad_perm:[1,0,3,2] row_mask:0xf bank_mask:0xf bound_ctrl:1
	v_add_f32_dpp v205, v205, v205 quad_perm:[1,0,3,2] row_mask:0xf bank_mask:0xf bound_ctrl:1
	v_pk_fma_f32 v[166:167], v[70:71], v[122:123], v[166:167] op_sel_hi:[1,0,1]
	v_pk_fma_f32 v[164:165], v[72:73], v[122:123], v[164:165] op_sel_hi:[1,0,1]
	v_add_f32_dpp v206, v206, v206 quad_perm:[1,0,3,2] row_mask:0xf bank_mask:0xf bound_ctrl:1
	v_add_f32_dpp v207, v207, v207 quad_perm:[1,0,3,2] row_mask:0xf bank_mask:0xf bound_ctrl:1
	s_waitcnt lgkmcnt(11)
; #define LAS __attribute__((address_space(3)))
; template <int CTRL> __device__ __forceinline__ float dpp_f(float x) { return __int_as_float(__builtin_amdgcn_update_dpp(0, __float_as_int(x), CTRL, 0xf, 0xf, false)); }
; __device__ __forceinline__ void phase_scan(const Params& p, LAS unsigned char* lds) {
;     ...
;                         for (int u16 = 0; u16 < 16; ++u16) {
;                             const int s = 16 * hb + u16;
;                             const int sn = (s + 1) & 31;
;                             const f32x4 a_n = *(const LAS f32x4*)(sA + sn * 64), w_n = *(const LAS f32x4*)(sW + sn * 64), b_n = *(const LAS f32x4*)(sB + sn * 64);
;                             const f32x4 k_n = *(const LAS f32x4*)(sK + sn * 64), r_n = *(const LAS f32x4*)(sR + sn * 64);
;                             const float v = vq[u16 >> 2][u16 & 3];
;                             const f32x2 vv = {v, v};
;                             f32x2 pp = S01 * (f32x2){a_[0], a_[1]}; pp = S23 * (f32x2){a_[2], a_[3]} + pp;
;                             f32x2 yy = S01 * (f32x2){rp[0], rp[1]}; yy = S23 * (f32x2){rp[2], rp[3]} + yy;
;                             float sa = pp[0] + pp[1], y = yy[0] + yy[1];
;                             sa += dpp_f<0xB1>(sa); y += dpp_f<0xB1>(y);
;                             sa += dpp_f<0x4E>(sa); y += dpp_f<0x4E>(y);
;                             sa += dpp_f<0x141>(sa); y += dpp_f<0x141>(y);
;                             sa += dpp_f<0x140>(sa); y += dpp_f<0x140>(y);
;                             sY[((s - 1) & 31) * 16 + srow] = y;
;                             const f32x2 sv = {sa, sa};
;                             S01 = S01 * (f32x2){w_[0], w_[1]} + vv * (f32x2){k_[0], k_[1]};
;                             S23 = S23 * (f32x2){w_[2], w_[3]} + vv * (f32x2){k_[2], k_[3]};
;                             S01 = sv * (f32x2){b_[0], b_[1]} + S01;
;                             S23 = sv * (f32x2){b_[2], b_[3]} + S23;
;                             rp = r_;
;                             a_ = a_n; w_ = w_n; b_ = b_n; k_ = k_n; r_ = r_n;
;                         }
	v_pk_mul_f32 v[114:115], v[166:167], v[2:3]
	v_pk_mul_f32 v[116:117], v[166:167], v[78:79]
	v_pk_fma_f32 v[114:115], v[164:165], v[4:5], v[114:115]
	v_pk_fma_f32 v[116:117], v[164:165], v[80:81], v[116:117]
	v_add_f32_e32 v122, v114, v115
	s_waitcnt lgkmcnt(10)
	v_pk_mul_f32 v[118:119], v[86:87], v[14:15] op_sel_hi:[0,1]
	v_add_f32_e32 v221, v116, v117
	ds_read_b128 v[74:77], v124 offset:18176
	ds_read_b128 v[66:69], v124 offset:9984
	ds_read_b128 v[70:73], v124 offset:34560
	ds_read_b128 v[78:81], v124 offset:1792
	ds_read_b128 v[62:65], v124 offset:26368
	v_add_f32_dpp v122, v122, v122 quad_perm:[1,0,3,2] row_mask:0xf bank_mask:0xf bound_ctrl:1
	v_pk_mul_f32 v[120:121], v[86:87], v[16:17] op_sel_hi:[0,1]
	v_add_f32_dpp v204, v204, v204 quad_perm:[2,3,0,1] row_mask:0xf bank_mask:0xf bound_ctrl:1
	v_add_f32_dpp v122, v122, v122 quad_perm:[2,3,0,1] row_mask:0xf bank_mask:0xf bound_ctrl:1
	v_pk_fma_f32 v[166:167], v[166:167], v[6:7], v[118:119]
	v_add_f32_dpp v205, v205, v205 quad_perm:[2,3,0,1] row_mask:0xf bank_mask:0xf bound_ctrl:1
	v_add_f32_dpp v122, v122, v122 row_half_mirror row_mask:0xf bank_mask:0xf bound_ctrl:1
	v_pk_fma_f32 v[164:165], v[164:165], v[8:9], v[120:121]
	v_add_f32_dpp v206, v206, v206 quad_perm:[2,3,0,1] row_mask:0xf bank_mask:0xf bound_ctrl:1
	v_add_f32_dpp v122, v122, v122 row_mirror row_mask:0xf bank_mask:0xf bound_ctrl:1
	v_add_f32_dpp v207, v207, v207 quad_perm:[2,3,0,1] row_mask:0xf bank_mask:0xf bound_ctrl:1
	v_cndmask_b32_e64 v202, v204, v205, s[34:35]
	v_pk_fma_f32 v[166:167], v[10:11], v[122:123], v[166:167] op_sel_hi:[1,0,1]
	v_pk_fma_f32 v[164:165], v[12:13], v[122:123], v[164:165] op_sel_hi:[1,0,1]
	v_cndmask_b32_e64 v202, v202, v206, s[56:57]
	v_cndmask_b32_e64 v202, v202, v207, s[98:99]
	s_waitcnt lgkmcnt(10)
	v_pk_mul_f32 v[114:115], v[166:167], v[22:23]
	v_pk_mul_f32 v[116:117], v[166:167], v[18:19]
	v_pk_fma_f32 v[114:115], v[164:165], v[24:25], v[114:115]
	v_pk_fma_f32 v[116:117], v[164:165], v[20:21], v[116:117]
	v_add_f32_e32 v122, v114, v115
	v_pk_mul_f32 v[118:119], v[86:87], v[34:35] op_sel:[1,0]
	v_add_f32_e32 v222, v116, v117
	ds_read_b128 v[14:17], v124 offset:18432
	ds_read_b128 v[6:9], v124 offset:10240
	ds_read_b128 v[10:13], v124 offset:34816
	ds_read_b128 v[18:21], v124 offset:2048
	ds_read_b128 v[2:5], v124 offset:26624
	ds_read_b128 v[90:93], v125 offset:40992
	v_add_f32_dpp v122, v122, v122 quad_perm:[1,0,3,2] row_mask:0xf bank_mask:0xf bound_ctrl:1
	v_pk_mul_f32 v[120:121], v[86:87], v[36:37] op_sel:[1,0]
	v_cvt_f16_f32_e32 v203, v202
	v_add_f32_dpp v122, v122, v122 quad_perm:[2,3,0,1] row_mask:0xf bank_mask:0xf bound_ctrl:1
	v_pk_fma_f32 v[166:167], v[166:167], v[26:27], v[118:119]
	s_mov_b64 exec, s[14:15]
	global_store_short v[128:129], v203, off
	s_mov_b64 exec, -1
	v_add_f32_dpp v122, v122, v122 row_half_mirror row_mask:0xf bank_mask:0xf bound_ctrl:1
	v_pk_fma_f32 v[164:165], v[164:165], v[28:29], v[120:121]
	v_lshl_add_u64 v[128:129], v[128:129], 0, s[100:101]
	v_add_f32_dpp v122, v122, v122 row_mirror row_mask:0xf bank_mask:0xf bound_ctrl:1
	s_nop 0
	v_pk_fma_f32 v[166:167], v[30:31], v[122:123], v[166:167] op_sel_hi:[1,0,1]
	v_pk_fma_f32 v[164:165], v[32:33], v[122:123], v[164:165] op_sel_hi:[1,0,1]
	s_waitcnt lgkmcnt(11)
	v_pk_mul_f32 v[114:115], v[166:167], v[42:43]
	v_pk_mul_f32 v[116:117], v[166:167], v[38:39]
	v_pk_fma_f32 v[114:115], v[164:165], v[44:45], v[114:115]
	v_pk_fma_f32 v[116:117], v[164:165], v[40:41], v[116:117]
	v_add_f32_e32 v122, v114, v115
	v_pk_mul_f32 v[118:119], v[88:89], v[54:55] op_sel_hi:[0,1]
	v_add_f32_e32 v223, v116, v117
	ds_read_b128 v[34:37], v124 offset:18688
	ds_read_b128 v[26:29], v124 offset:10496
	ds_read_b128 v[30:33], v124 offset:35072
	ds_read_b128 v[38:41], v124 offset:2304
	ds_read_b128 v[22:25], v124 offset:26880
	v_add_f32_dpp v122, v122, v122 quad_perm:[1,0,3,2] row_mask:0xf bank_mask:0xf bound_ctrl:1
	v_pk_mul_f32 v[120:121], v[88:89], v[56:57] op_sel_hi:[0,1]
	s_nop 0
	v_add_f32_dpp v122, v122, v122 quad_perm:[2,3,0,1] row_mask:0xf bank_mask:0xf bound_ctrl:1
	v_pk_fma_f32 v[166:167], v[166:167], v[46:47], v[118:119]
	s_nop 0
	v_add_f32_dpp v122, v122, v122 row_half_mirror row_mask:0xf bank_mask:0xf bound_ctrl:1
	v_pk_fma_f32 v[164:165], v[164:165], v[48:49], v[120:121]
	s_nop 0
	v_add_f32_dpp v122, v122, v122 row_mirror row_mask:0xf bank_mask:0xf bound_ctrl:1
	s_nop 0
	v_pk_fma_f32 v[166:167], v[50:51], v[122:123], v[166:167] op_sel_hi:[1,0,1]
	v_pk_fma_f32 v[164:165], v[52:53], v[122:123], v[164:165] op_sel_hi:[1,0,1]
	s_waitcnt lgkmcnt(11)
	v_pk_mul_f32 v[114:115], v[166:167], v[62:63]
	v_pk_mul_f32 v[116:117], v[166:167], v[58:59]
	v_pk_fma_f32 v[114:115], v[164:165], v[64:65], v[114:115]
	v_pk_fma_f32 v[116:117], v[164:165], v[60:61], v[116:117]
	v_add_f32_e32 v122, v114, v115
	v_pk_mul_f32 v[118:119], v[88:89], v[74:75] op_sel:[1,0]
	v_add_f32_e32 v224, v116, v117
	ds_read_b128 v[54:57], v124 offset:18944
	ds_read_b128 v[46:49], v124 offset:10752
	ds_read_b128 v[50:53], v124 offset:35328
	ds_read_b128 v[58:61], v124 offset:2560
	ds_read_b128 v[42:45], v124 offset:27136
	v_add_f32_dpp v122, v122, v122 quad_perm:[1,0,3,2] row_mask:0xf bank_mask:0xf bound_ctrl:1
	v_pk_mul_f32 v[120:121], v[88:89], v[76:77] op_sel:[1,0]
	s_nop 0
	v_add_f32_dpp v122, v122, v122 quad_perm:[2,3,0,1] row_mask:0xf bank_mask:0xf bound_ctrl:1
	v_pk_fma_f32 v[166:167], v[166:167], v[66:67], v[118:119]
	s_nop 0
	v_add_f32_dpp v122, v122, v122 row_half_mirror row_mask:0xf bank_mask:0xf bound_ctrl:1
	v_pk_fma_f32 v[164:165], v[164:165], v[68:69], v[120:121]
	s_nop 0
	v_add_f32_dpp v122, v122, v122 row_mirror row_mask:0xf bank_mask:0xf bound_ctrl:1
	s_nop 0
	v_pk_fma_f32 v[166:167], v[70:71], v[122:123], v[166:167] op_sel_hi:[1,0,1]
	v_pk_fma_f32 v[164:165], v[72:73], v[122:123], v[164:165] op_sel_hi:[1,0,1]
	s_waitcnt lgkmcnt(11)
; #define LAS __attribute__((address_space(3)))
; template <int CTRL> __device__ __forceinline__ float dpp_f(float x) { return __int_as_float(__builtin_amdgcn_update_dpp(0, __float_as_int(x), CTRL, 0xf, 0xf, false)); }
; __device__ __forceinline__ void phase_scan(const Params& p, LAS unsigned char* lds) {
;     ...
;                         for (int u16 = 0; u16 < 16; ++u16) {
;                             const int s = 16 * hb + u16;
;                             const int sn = (s + 1) & 31;
;                             const f32x4 a_n = *(const LAS f32x4*)(sA + sn * 64), w_n = *(const LAS f32x4*)(sW + sn * 64), b_n = *(const LAS f32x4*)(sB + sn * 64);
;                             const f32x4 k_n = *(const LAS f32x4*)(sK + sn * 64), r_n = *(const LAS f32x4*)(sR + sn * 64);
;                             const float v = vq[u16 >> 2][u16 & 3];
;                             const f32x2 vv = {v, v};
;                             f32x2 pp = S01 * (f32x2){a_[0], a_[1]}; pp = S23 * (f32x2){a_[2], a_[3]} + pp;
;                             f32x2 yy = S01 * (f32x2){rp[0], rp[1]}; yy = S23 * (f32x2){rp[2], rp[3]} + yy;
;                             float sa = pp[0] + pp[1], y = yy[0] + yy[1];
;                             sa += dpp_f<0xB1>(sa); y += dpp_f<0xB1>(y);
;                             sa += dpp_f<0x4E>(sa); y += dpp_f<0x4E>(y);
;                             sa += dpp_f<0x141>(sa); y += dpp_f<0x141>(y);
;                             sa += dpp_f<0x140>(sa); y += dpp_f<0x140>(y);
;                             sY[((s - 1) & 31) * 16 + srow] = y;
;                             const f32x2 sv = {sa, sa};
;                             S01 = S01 * (f32x2){w_[0], w_[1]} + vv * (f32x2){k_[0], k_[1]};
;                             S23 = S23 * (f32x2){w_[2], w_[3]} + vv * (f32x2){k_[2], k_[3]};
;                             S01 = sv * (f32x2){b_[0], b_[1]} + S01;
;                             S23 = sv * (f32x2){b_[2], b_[3]} + S23;
;                             rp = r_;
;                             a_ = a_n; w_ = w_n; b_ = b_n; k_ = k_n; r_ = r_n;
;                         }
	v_pk_mul_f32 v[114:115], v[166:167], v[2:3]
	v_pk_mul_f32 v[116:117], v[166:167], v[78:79]
	v_pk_fma_f32 v[114:115], v[164:165], v[4:5], v[114:115]
	v_pk_fma_f32 v[116:117], v[164:165], v[80:81], v[116:117]
	v_add_f32_e32 v122, v114, v115
	s_waitcnt lgkmcnt(10)
	v_pk_mul_f32 v[118:119], v[90:91], v[14:15] op_sel_hi:[0,1]
	v_add_f32_e32 v225, v116, v117
	ds_read_b128 v[74:77], v124 offset:19200
	ds_read_b128 v[66:69], v124 offset:11008
	ds_read_b128 v[70:73], v124 offset:35584
	ds_read_b128 v[78:81], v124 offset:2816
	ds_read_b128 v[62:65], v124 offset:27392
	v_add_f32_dpp v122, v122, v122 quad_perm:[1,0,3,2] row_mask:0xf bank_mask:0xf bound_ctrl:1
	v_pk_mul_f32 v[120:121], v[90:91], v[16:17] op_sel_hi:[0,1]
	s_nop 0
	v_add_f32_dpp v122, v122, v122 quad_perm:[2,3,0,1] row_mask:0xf bank_mask:0xf bound_ctrl:1
	v_pk_fma_f32 v[166:167], v[166:167], v[6:7], v[118:119]
	s_nop 0
	v_add_f32_dpp v122, v122, v122 row_half_mirror row_mask:0xf bank_mask:0xf bound_ctrl:1
	v_pk_fma_f32 v[164:165], v[164:165], v[8:9], v[120:121]
	s_nop 0
	v_add_f32_dpp v122, v122, v122 row_mirror row_mask:0xf bank_mask:0xf bound_ctrl:1
	s_nop 0
	v_pk_fma_f32 v[166:167], v[10:11], v[122:123], v[166:167] op_sel_hi:[1,0,1]
	v_pk_fma_f32 v[164:165], v[12:13], v[122:123], v[164:165] op_sel_hi:[1,0,1]
	s_waitcnt lgkmcnt(10)
	v_pk_mul_f32 v[114:115], v[166:167], v[22:23]
	v_pk_mul_f32 v[116:117], v[166:167], v[18:19]
	v_pk_fma_f32 v[114:115], v[164:165], v[24:25], v[114:115]
	v_pk_fma_f32 v[116:117], v[164:165], v[20:21], v[116:117]
	v_add_f32_e32 v122, v114, v115
	v_pk_mul_f32 v[118:119], v[90:91], v[34:35] op_sel:[1,0]
	v_add_f32_e32 v226, v116, v117
	ds_read_b128 v[14:17], v124 offset:19456
	ds_read_b128 v[6:9], v124 offset:11264
	ds_read_b128 v[10:13], v124 offset:35840
	ds_read_b128 v[18:21], v124 offset:3072
	ds_read_b128 v[2:5], v124 offset:27648
	ds_read_b128 v[94:97], v125 offset:41008
	v_add_f32_dpp v122, v122, v122 quad_perm:[1,0,3,2] row_mask:0xf bank_mask:0xf bound_ctrl:1
	v_pk_mul_f32 v[120:121], v[90:91], v[36:37] op_sel:[1,0]
	s_nop 0
	v_add_f32_dpp v122, v122, v122 quad_perm:[2,3,0,1] row_mask:0xf bank_mask:0xf bound_ctrl:1
	v_pk_fma_f32 v[166:167], v[166:167], v[26:27], v[118:119]
	s_nop 0
	v_add_f32_dpp v122, v122, v122 row_half_mirror row_mask:0xf bank_mask:0xf bound_ctrl:1
	v_pk_fma_f32 v[164:165], v[164:165], v[28:29], v[120:121]
	s_nop 0
	v_add_f32_dpp v122, v122, v122 row_mirror row_mask:0xf bank_mask:0xf bound_ctrl:1
	s_nop 0
	v_pk_fma_f32 v[166:167], v[30:31], v[122:123], v[166:167] op_sel_hi:[1,0,1]
	v_pk_fma_f32 v[164:165], v[32:33], v[122:123], v[164:165] op_sel_hi:[1,0,1]
	s_waitcnt lgkmcnt(11)
	v_pk_mul_f32 v[114:115], v[166:167], v[42:43]
	v_pk_mul_f32 v[116:117], v[166:167], v[38:39]
	v_pk_fma_f32 v[114:115], v[164:165], v[44:45], v[114:115]
	v_pk_fma_f32 v[116:117], v[164:165], v[40:41], v[116:117]
	v_add_f32_e32 v122, v114, v115
	v_pk_mul_f32 v[118:119], v[92:93], v[54:55] op_sel_hi:[0,1]
	v_add_f32_e32 v227, v116, v117
	ds_read_b128 v[34:37], v124 offset:19712
	ds_read_b128 v[26:29], v124 offset:11520
	ds_read_b128 v[30:33], v124 offset:36096
	ds_read_b128 v[38:41], v124 offset:3328
	ds_read_b128 v[22:25], v124 offset:27904
	v_add_f32_dpp v122, v122, v122 quad_perm:[1,0,3,2] row_mask:0xf bank_mask:0xf bound_ctrl:1
	v_pk_mul_f32 v[120:121], v[92:93], v[56:57] op_sel_hi:[0,1]
	s_nop 0
	v_add_f32_dpp v122, v122, v122 quad_perm:[2,3,0,1] row_mask:0xf bank_mask:0xf bound_ctrl:1
	v_pk_fma_f32 v[166:167], v[166:167], v[46:47], v[118:119]
	s_nop 0
	v_add_f32_dpp v122, v122, v122 row_half_mirror row_mask:0xf bank_mask:0xf bound_ctrl:1
	v_pk_fma_f32 v[164:165], v[164:165], v[48:49], v[120:121]
	s_nop 0
	v_add_f32_dpp v122, v122, v122 row_mirror row_mask:0xf bank_mask:0xf bound_ctrl:1
	s_nop 0
	v_pk_fma_f32 v[166:167], v[50:51], v[122:123], v[166:167] op_sel_hi:[1,0,1]
	v_pk_fma_f32 v[164:165], v[52:53], v[122:123], v[164:165] op_sel_hi:[1,0,1]
	s_waitcnt lgkmcnt(11)
	v_pk_mul_f32 v[114:115], v[166:167], v[62:63]
	v_pk_mul_f32 v[116:117], v[166:167], v[58:59]
	v_pk_fma_f32 v[114:115], v[164:165], v[64:65], v[114:115]
	v_pk_fma_f32 v[116:117], v[164:165], v[60:61], v[116:117]
	v_add_f32_e32 v122, v114, v115
	v_pk_mul_f32 v[118:119], v[92:93], v[74:75] op_sel:[1,0]
	v_add_f32_e32 v228, v116, v117
	ds_read_b128 v[54:57], v124 offset:19968
	ds_read_b128 v[46:49], v124 offset:11776
	ds_read_b128 v[50:53], v124 offset:36352
	ds_read_b128 v[58:61], v124 offset:3584
	ds_read_b128 v[42:45], v124 offset:28160
	v_add_f32_dpp v122, v122, v122 quad_perm:[1,0,3,2] row_mask:0xf bank_mask:0xf bound_ctrl:1
	v_pk_mul_f32 v[120:121], v[92:93], v[76:77] op_sel:[1,0]
	v_add_f32_dpp v220, v220, v220 row_mirror row_mask:0xf bank_mask:0xf bound_ctrl:1
	v_add_f32_dpp v122, v122, v122 quad_perm:[2,3,0,1] row_mask:0xf bank_mask:0xf bound_ctrl:1
	v_pk_fma_f32 v[166:167], v[166:167], v[66:67], v[118:119]
	v_add_f32_dpp v220, v228, v228 row_mirror row_mask:0xf bank_mask:0xc bound_ctrl:1
	v_add_f32_dpp v122, v122, v122 row_half_mirror row_mask:0xf bank_mask:0xf bound_ctrl:1
	v_pk_fma_f32 v[164:165], v[164:165], v[68:69], v[120:121]
	s_nop 0
	v_add_f32_dpp v122, v122, v122 row_mirror row_mask:0xf bank_mask:0xf bound_ctrl:1
	s_nop 0
	v_pk_fma_f32 v[166:167], v[70:71], v[122:123], v[166:167] op_sel_hi:[1,0,1]
	v_pk_fma_f32 v[164:165], v[72:73], v[122:123], v[164:165] op_sel_hi:[1,0,1]
	s_waitcnt lgkmcnt(11)
	v_pk_mul_f32 v[114:115], v[166:167], v[2:3]
	v_pk_mul_f32 v[116:117], v[166:167], v[78:79]
	v_pk_fma_f32 v[114:115], v[164:165], v[4:5], v[114:115]
	v_pk_fma_f32 v[116:117], v[164:165], v[80:81], v[116:117]
	v_add_f32_e32 v122, v114, v115
	s_waitcnt lgkmcnt(10)
; #define LAS __attribute__((address_space(3)))
; template <int CTRL> __device__ __forceinline__ float dpp_f(float x) { return __int_as_float(__builtin_amdgcn_update_dpp(0, __float_as_int(x), CTRL, 0xf, 0xf, false)); }
; __device__ __forceinline__ void phase_scan(const Params& p, LAS unsigned char* lds) {
;     ...
;                         for (int u16 = 0; u16 < 16; ++u16) {
;                             const int s = 16 * hb + u16;
;                             const int sn = (s + 1) & 31;
;                             const f32x4 a_n = *(const LAS f32x4*)(sA + sn * 64), w_n = *(const LAS f32x4*)(sW + sn * 64), b_n = *(const LAS f32x4*)(sB + sn * 64);
;                             const f32x4 k_n = *(const LAS f32x4*)(sK + sn * 64), r_n = *(const LAS f32x4*)(sR + sn * 64);
;                             const float v = vq[u16 >> 2][u16 & 3];
;                             const f32x2 vv = {v, v};
;                             f32x2 pp = S01 * (f32x2){a_[0], a_[1]}; pp = S23 * (f32x2){a_[2], a_[3]} + pp;
;                             f32x2 yy = S01 * (f32x2){rp[0], rp[1]}; yy = S23 * (f32x2){rp[2], rp[3]} + yy;
;                             float sa = pp[0] + pp[1], y = yy[0] + yy[1];
;                             sa += dpp_f<0xB1>(sa); y += dpp_f<0xB1>(y);
;                             sa += dpp_f<0x4E>(sa); y += dpp_f<0x4E>(y);
;                             sa += dpp_f<0x141>(sa); y += dpp_f<0x141>(y);
;                             sa += dpp_f<0x140>(sa); y += dpp_f<0x140>(y);
;                             sY[((s - 1) & 31) * 16 + srow] = y;
;                             const f32x2 sv = {sa, sa};
;                             S01 = S01 * (f32x2){w_[0], w_[1]} + vv * (f32x2){k_[0], k_[1]};
;                             S23 = S23 * (f32x2){w_[2], w_[3]} + vv * (f32x2){k_[2], k_[3]};
;                             S01 = sv * (f32x2){b_[0], b_[1]} + S01;
;                             S23 = sv * (f32x2){b_[2], b_[3]} + S23;
;                             rp = r_;
;                             a_ = a_n; w_ = w_n; b_ = b_n; k_ = k_n; r_ = r_n;
;                         }
	v_pk_mul_f32 v[118:119], v[94:95], v[14:15] op_sel_hi:[0,1]
	v_add_f32_e32 v229, v116, v117
	ds_read_b128 v[74:77], v124 offset:20224
	ds_read_b128 v[66:69], v124 offset:12032
	ds_read_b128 v[70:73], v124 offset:36608
	ds_read_b128 v[78:81], v124 offset:3840
	ds_read_b128 v[62:65], v124 offset:28416
	v_add_f32_dpp v122, v122, v122 quad_perm:[1,0,3,2] row_mask:0xf bank_mask:0xf bound_ctrl:1
	v_pk_mul_f32 v[120:121], v[94:95], v[16:17] op_sel_hi:[0,1]
	v_add_f32_dpp v221, v221, v221 row_mirror row_mask:0xf bank_mask:0xf bound_ctrl:1
	v_add_f32_dpp v122, v122, v122 quad_perm:[2,3,0,1] row_mask:0xf bank_mask:0xf bound_ctrl:1
	v_pk_fma_f32 v[166:167], v[166:167], v[6:7], v[118:119]
	v_add_f32_dpp v221, v229, v229 row_mirror row_mask:0xf bank_mask:0xc bound_ctrl:1
	v_add_f32_dpp v122, v122, v122 row_half_mirror row_mask:0xf bank_mask:0xf bound_ctrl:1
	v_pk_fma_f32 v[164:165], v[164:165], v[8:9], v[120:121]
	s_nop 0
	v_add_f32_dpp v122, v122, v122 row_mirror row_mask:0xf bank_mask:0xf bound_ctrl:1
	s_nop 0
	v_pk_fma_f32 v[166:167], v[10:11], v[122:123], v[166:167] op_sel_hi:[1,0,1]
	v_pk_fma_f32 v[164:165], v[12:13], v[122:123], v[164:165] op_sel_hi:[1,0,1]
	s_waitcnt lgkmcnt(10)
	v_pk_mul_f32 v[114:115], v[166:167], v[22:23]
	v_pk_mul_f32 v[116:117], v[166:167], v[18:19]
	v_pk_fma_f32 v[114:115], v[164:165], v[24:25], v[114:115]
	v_pk_fma_f32 v[116:117], v[164:165], v[20:21], v[116:117]
	v_add_f32_e32 v122, v114, v115
	v_pk_mul_f32 v[118:119], v[94:95], v[34:35] op_sel:[1,0]
	v_add_f32_e32 v230, v116, v117
	ds_read_b128 v[14:17], v124 offset:20480
	ds_read_b128 v[6:9], v124 offset:12288
	ds_read_b128 v[10:13], v124 offset:36864
	ds_read_b128 v[18:21], v124 offset:4096
	ds_read_b128 v[2:5], v124 offset:28672
	ds_read_b128 v[98:101], v125 offset:41024
	v_add_f32_dpp v122, v122, v122 quad_perm:[1,0,3,2] row_mask:0xf bank_mask:0xf bound_ctrl:1
	v_pk_mul_f32 v[120:121], v[94:95], v[36:37] op_sel:[1,0]
	v_add_f32_dpp v222, v222, v222 row_mirror row_mask:0xf bank_mask:0xf bound_ctrl:1
	v_add_f32_dpp v122, v122, v122 quad_perm:[2,3,0,1] row_mask:0xf bank_mask:0xf bound_ctrl:1
	v_pk_fma_f32 v[166:167], v[166:167], v[26:27], v[118:119]
	v_add_f32_dpp v222, v230, v230 row_mirror row_mask:0xf bank_mask:0xc bound_ctrl:1
	v_add_f32_dpp v122, v122, v122 row_half_mirror row_mask:0xf bank_mask:0xf bound_ctrl:1
	v_pk_fma_f32 v[164:165], v[164:165], v[28:29], v[120:121]
	s_nop 0
	v_add_f32_dpp v122, v122, v122 row_mirror row_mask:0xf bank_mask:0xf bound_ctrl:1
	s_nop 0
	v_pk_fma_f32 v[166:167], v[30:31], v[122:123], v[166:167] op_sel_hi:[1,0,1]
	v_pk_fma_f32 v[164:165], v[32:33], v[122:123], v[164:165] op_sel_hi:[1,0,1]
	s_waitcnt lgkmcnt(11)
	v_pk_mul_f32 v[114:115], v[166:167], v[42:43]
	v_pk_mul_f32 v[116:117], v[166:167], v[38:39]
	v_pk_fma_f32 v[114:115], v[164:165], v[44:45], v[114:115]
	v_pk_fma_f32 v[116:117], v[164:165], v[40:41], v[116:117]
	v_add_f32_e32 v122, v114, v115
	v_pk_mul_f32 v[118:119], v[96:97], v[54:55] op_sel_hi:[0,1]
	v_add_f32_e32 v231, v116, v117
	ds_read_b128 v[34:37], v124 offset:20736
	ds_read_b128 v[26:29], v124 offset:12544
	ds_read_b128 v[30:33], v124 offset:37120
	ds_read_b128 v[38:41], v124 offset:4352
	ds_read_b128 v[22:25], v124 offset:28928
	v_add_f32_dpp v122, v122, v122 quad_perm:[1,0,3,2] row_mask:0xf bank_mask:0xf bound_ctrl:1
	v_pk_mul_f32 v[120:121], v[96:97], v[56:57] op_sel_hi:[0,1]
	v_add_f32_dpp v223, v223, v223 row_mirror row_mask:0xf bank_mask:0xf bound_ctrl:1
	v_add_f32_dpp v122, v122, v122 quad_perm:[2,3,0,1] row_mask:0xf bank_mask:0xf bound_ctrl:1
	v_pk_fma_f32 v[166:167], v[166:167], v[46:47], v[118:119]
	v_add_f32_dpp v223, v231, v231 row_mirror row_mask:0xf bank_mask:0xc bound_ctrl:1
	v_add_f32_dpp v122, v122, v122 row_half_mirror row_mask:0xf bank_mask:0xf bound_ctrl:1
	v_pk_fma_f32 v[164:165], v[164:165], v[48:49], v[120:121]
	s_nop 0
	v_add_f32_dpp v122, v122, v122 row_mirror row_mask:0xf bank_mask:0xf bound_ctrl:1
	s_nop 0
	v_pk_fma_f32 v[166:167], v[50:51], v[122:123], v[166:167] op_sel_hi:[1,0,1]
	v_pk_fma_f32 v[164:165], v[52:53], v[122:123], v[164:165] op_sel_hi:[1,0,1]
	s_waitcnt lgkmcnt(11)
	v_pk_mul_f32 v[114:115], v[166:167], v[62:63]
	v_pk_mul_f32 v[116:117], v[166:167], v[58:59]
	v_pk_fma_f32 v[114:115], v[164:165], v[64:65], v[114:115]
	v_pk_fma_f32 v[116:117], v[164:165], v[60:61], v[116:117]
	v_add_f32_e32 v122, v114, v115
	v_pk_mul_f32 v[118:119], v[96:97], v[74:75] op_sel:[1,0]
	v_add_f32_e32 v232, v116, v117
	ds_read_b128 v[54:57], v124 offset:20992
	ds_read_b128 v[46:49], v124 offset:12800
	ds_read_b128 v[50:53], v124 offset:37376
	ds_read_b128 v[58:61], v124 offset:4608
	ds_read_b128 v[42:45], v124 offset:29184
	v_add_f32_dpp v122, v122, v122 quad_perm:[1,0,3,2] row_mask:0xf bank_mask:0xf bound_ctrl:1
	v_pk_mul_f32 v[120:121], v[96:97], v[76:77] op_sel:[1,0]
	v_add_f32_dpp v224, v224, v224 row_mirror row_mask:0xf bank_mask:0xf bound_ctrl:1
	v_add_f32_dpp v122, v122, v122 quad_perm:[2,3,0,1] row_mask:0xf bank_mask:0xf bound_ctrl:1
	v_pk_fma_f32 v[166:167], v[166:167], v[66:67], v[118:119]
	v_add_f32_dpp v224, v232, v232 row_mirror row_mask:0xf bank_mask:0xc bound_ctrl:1
	v_add_f32_dpp v122, v122, v122 row_half_mirror row_mask:0xf bank_mask:0xf bound_ctrl:1
	v_pk_fma_f32 v[164:165], v[164:165], v[68:69], v[120:121]
	s_nop 0
	v_add_f32_dpp v122, v122, v122 row_mirror row_mask:0xf bank_mask:0xf bound_ctrl:1
	s_nop 0
	v_pk_fma_f32 v[166:167], v[70:71], v[122:123], v[166:167] op_sel_hi:[1,0,1]
	v_pk_fma_f32 v[164:165], v[72:73], v[122:123], v[164:165] op_sel_hi:[1,0,1]
	s_waitcnt lgkmcnt(11)
; #define LAS __attribute__((address_space(3)))
; template <int CTRL> __device__ __forceinline__ float dpp_f(float x) { return __int_as_float(__builtin_amdgcn_update_dpp(0, __float_as_int(x), CTRL, 0xf, 0xf, false)); }
; __device__ __forceinline__ void phase_scan(const Params& p, LAS unsigned char* lds) {
;     ...
;                         for (int u16 = 0; u16 < 16; ++u16) {
;                             const int s = 16 * hb + u16;
;                             const int sn = (s + 1) & 31;
;                             const f32x4 a_n = *(const LAS f32x4*)(sA + sn * 64), w_n = *(const LAS f32x4*)(sW + sn * 64), b_n = *(const LAS f32x4*)(sB + sn * 64);
;                             const f32x4 k_n = *(const LAS f32x4*)(sK + sn * 64), r_n = *(const LAS f32x4*)(sR + sn * 64);
;                             const float v = vq[u16 >> 2][u16 & 3];
;                             const f32x2 vv = {v, v};
;                             f32x2 pp = S01 * (f32x2){a_[0], a_[1]}; pp = S23 * (f32x2){a_[2], a_[3]} + pp;
;                             f32x2 yy = S01 * (f32x2){rp[0], rp[1]}; yy = S23 * (f32x2){rp[2], rp[3]} + yy;
;                             float sa = pp[0] + pp[1], y = yy[0] + yy[1];
;                             sa += dpp_f<0xB1>(sa); y += dpp_f<0xB1>(y);
;                             sa += dpp_f<0x4E>(sa); y += dpp_f<0x4E>(y);
;                             sa += dpp_f<0x141>(sa); y += dpp_f<0x141>(y);
;                             sa += dpp_f<0x140>(sa); y += dpp_f<0x140>(y);
;                             sY[((s - 1) & 31) * 16 + srow] = y;
;                             const f32x2 sv = {sa, sa};
;                             S01 = S01 * (f32x2){w_[0], w_[1]} + vv * (f32x2){k_[0], k_[1]};
;                             S23 = S23 * (f32x2){w_[2], w_[3]} + vv * (f32x2){k_[2], k_[3]};
;                             S01 = sv * (f32x2){b_[0], b_[1]} + S01;
;                             S23 = sv * (f32x2){b_[2], b_[3]} + S23;
;                             rp = r_;
;                             a_ = a_n; w_ = w_n; b_ = b_n; k_ = k_n; r_ = r_n;
;                         }
	v_pk_mul_f32 v[114:115], v[166:167], v[2:3]
	v_pk_mul_f32 v[116:117], v[166:167], v[78:79]
	v_pk_fma_f32 v[114:115], v[164:165], v[4:5], v[114:115]
	v_pk_fma_f32 v[116:117], v[164:165], v[80:81], v[116:117]
	v_add_f32_e32 v122, v114, v115
	s_waitcnt lgkmcnt(10)
	v_pk_mul_f32 v[118:119], v[98:99], v[14:15] op_sel_hi:[0,1]
	v_add_f32_e32 v233, v116, v117
	ds_read_b128 v[74:77], v124 offset:21248
	ds_read_b128 v[66:69], v124 offset:13056
	ds_read_b128 v[70:73], v124 offset:37632
	ds_read_b128 v[78:81], v124 offset:4864
	ds_read_b128 v[62:65], v124 offset:29440
	v_add_f32_dpp v122, v122, v122 quad_perm:[1,0,3,2] row_mask:0xf bank_mask:0xf bound_ctrl:1
	v_pk_mul_f32 v[120:121], v[98:99], v[16:17] op_sel_hi:[0,1]
	v_add_f32_dpp v225, v225, v225 row_mirror row_mask:0xf bank_mask:0xf bound_ctrl:1
	v_add_f32_dpp v122, v122, v122 quad_perm:[2,3,0,1] row_mask:0xf bank_mask:0xf bound_ctrl:1
	v_pk_fma_f32 v[166:167], v[166:167], v[6:7], v[118:119]
	v_add_f32_dpp v225, v233, v233 row_mirror row_mask:0xf bank_mask:0xc bound_ctrl:1
	v_add_f32_dpp v122, v122, v122 row_half_mirror row_mask:0xf bank_mask:0xf bound_ctrl:1
	v_pk_fma_f32 v[164:165], v[164:165], v[8:9], v[120:121]
	s_nop 0
	v_add_f32_dpp v122, v122, v122 row_mirror row_mask:0xf bank_mask:0xf bound_ctrl:1
	s_nop 0
	v_pk_fma_f32 v[166:167], v[10:11], v[122:123], v[166:167] op_sel_hi:[1,0,1]
	v_pk_fma_f32 v[164:165], v[12:13], v[122:123], v[164:165] op_sel_hi:[1,0,1]
	s_waitcnt lgkmcnt(10)
	v_pk_mul_f32 v[114:115], v[166:167], v[22:23]
	v_pk_mul_f32 v[116:117], v[166:167], v[18:19]
	v_pk_fma_f32 v[114:115], v[164:165], v[24:25], v[114:115]
	v_pk_fma_f32 v[116:117], v[164:165], v[20:21], v[116:117]
	v_add_f32_e32 v122, v114, v115
	v_pk_mul_f32 v[118:119], v[98:99], v[34:35] op_sel:[1,0]
	v_add_f32_e32 v234, v116, v117
	ds_read_b128 v[14:17], v124 offset:21504
	ds_read_b128 v[6:9], v124 offset:13312
	ds_read_b128 v[10:13], v124 offset:37888
	ds_read_b128 v[18:21], v124 offset:5120
	ds_read_b128 v[2:5], v124 offset:29696
	ds_read_b128 v[102:105], v125 offset:41040
	v_add_f32_dpp v122, v122, v122 quad_perm:[1,0,3,2] row_mask:0xf bank_mask:0xf bound_ctrl:1
	v_pk_mul_f32 v[120:121], v[98:99], v[36:37] op_sel:[1,0]
	v_add_f32_dpp v226, v226, v226 row_mirror row_mask:0xf bank_mask:0xf bound_ctrl:1
	v_add_f32_dpp v122, v122, v122 quad_perm:[2,3,0,1] row_mask:0xf bank_mask:0xf bound_ctrl:1
	v_pk_fma_f32 v[166:167], v[166:167], v[26:27], v[118:119]
	v_add_f32_dpp v226, v234, v234 row_mirror row_mask:0xf bank_mask:0xc bound_ctrl:1
	v_add_f32_dpp v122, v122, v122 row_half_mirror row_mask:0xf bank_mask:0xf bound_ctrl:1
	v_pk_fma_f32 v[164:165], v[164:165], v[28:29], v[120:121]
	s_nop 0
	v_add_f32_dpp v122, v122, v122 row_mirror row_mask:0xf bank_mask:0xf bound_ctrl:1
	s_nop 0
	v_pk_fma_f32 v[166:167], v[30:31], v[122:123], v[166:167] op_sel_hi:[1,0,1]
	v_pk_fma_f32 v[164:165], v[32:33], v[122:123], v[164:165] op_sel_hi:[1,0,1]
	s_waitcnt lgkmcnt(11)
	v_pk_mul_f32 v[114:115], v[166:167], v[42:43]
	v_pk_mul_f32 v[116:117], v[166:167], v[38:39]
	v_pk_fma_f32 v[114:115], v[164:165], v[44:45], v[114:115]
	v_pk_fma_f32 v[116:117], v[164:165], v[40:41], v[116:117]
	v_add_f32_e32 v122, v114, v115
	v_pk_mul_f32 v[118:119], v[100:101], v[54:55] op_sel_hi:[0,1]
	v_add_f32_e32 v235, v116, v117
	ds_read_b128 v[34:37], v124 offset:21760
	ds_read_b128 v[26:29], v124 offset:13568
	ds_read_b128 v[30:33], v124 offset:38144
	ds_read_b128 v[38:41], v124 offset:5376
	ds_read_b128 v[22:25], v124 offset:29952
	v_add_f32_dpp v122, v122, v122 quad_perm:[1,0,3,2] row_mask:0xf bank_mask:0xf bound_ctrl:1
	v_pk_mul_f32 v[120:121], v[100:101], v[56:57] op_sel_hi:[0,1]
	v_add_f32_dpp v227, v227, v227 row_mirror row_mask:0xf bank_mask:0xf bound_ctrl:1
	v_add_f32_dpp v122, v122, v122 quad_perm:[2,3,0,1] row_mask:0xf bank_mask:0xf bound_ctrl:1
	v_pk_fma_f32 v[166:167], v[166:167], v[46:47], v[118:119]
	v_add_f32_dpp v227, v235, v235 row_mirror row_mask:0xf bank_mask:0xc bound_ctrl:1
	v_add_f32_dpp v122, v122, v122 row_half_mirror row_mask:0xf bank_mask:0xf bound_ctrl:1
	v_pk_fma_f32 v[164:165], v[164:165], v[48:49], v[120:121]
	v_add_f32_dpp v220, v220, v220 row_half_mirror row_mask:0xf bank_mask:0xf bound_ctrl:1
	v_add_f32_dpp v122, v122, v122 row_mirror row_mask:0xf bank_mask:0xf bound_ctrl:1
	v_add_f32_dpp v221, v221, v221 row_half_mirror row_mask:0xf bank_mask:0xf bound_ctrl:1
	v_add_f32_dpp v222, v222, v222 row_half_mirror row_mask:0xf bank_mask:0xf bound_ctrl:1
	v_pk_fma_f32 v[166:167], v[50:51], v[122:123], v[166:167] op_sel_hi:[1,0,1]
	v_pk_fma_f32 v[164:165], v[52:53], v[122:123], v[164:165] op_sel_hi:[1,0,1]
	v_add_f32_dpp v223, v223, v223 row_half_mirror row_mask:0xf bank_mask:0xf bound_ctrl:1
	v_add_f32_dpp v220, v224, v224 row_half_mirror row_mask:0xf bank_mask:0xa bound_ctrl:1
	s_waitcnt lgkmcnt(11)
; #define LAS __attribute__((address_space(3)))
; template <int CTRL> __device__ __forceinline__ float dpp_f(float x) { return __int_as_float(__builtin_amdgcn_update_dpp(0, __float_as_int(x), CTRL, 0xf, 0xf, false)); }
; __device__ __forceinline__ void phase_scan(const Params& p, LAS unsigned char* lds) {
;     ...
;                         for (int u16 = 0; u16 < 16; ++u16) {
;                             const int s = 16 * hb + u16;
;                             const int sn = (s + 1) & 31;
;                             const f32x4 a_n = *(const LAS f32x4*)(sA + sn * 64), w_n = *(const LAS f32x4*)(sW + sn * 64), b_n = *(const LAS f32x4*)(sB + sn * 64);
;                             const f32x4 k_n = *(const LAS f32x4*)(sK + sn * 64), r_n = *(const LAS f32x4*)(sR + sn * 64);
;                             const float v = vq[u16 >> 2][u16 & 3];
;                             const f32x2 vv = {v, v};
;                             f32x2 pp = S01 * (f32x2){a_[0], a_[1]}; pp = S23 * (f32x2){a_[2], a_[3]} + pp;
;                             f32x2 yy = S01 * (f32x2){rp[0], rp[1]}; yy = S23 * (f32x2){rp[2], rp[3]} + yy;
;                             float sa = pp[0] + pp[1], y = yy[0] + yy[1];
;                             sa += dpp_f<0xB1>(sa); y += dpp_f<0xB1>(y);
;                             sa += dpp_f<0x4E>(sa); y += dpp_f<0x4E>(y);
;                             sa += dpp_f<0x141>(sa); y += dpp_f<0x141>(y);
;                             sa += dpp_f<0x140>(sa); y += dpp_f<0x140>(y);
;                             sY[((s - 1) & 31) * 16 + srow] = y;
;                             const f32x2 sv = {sa, sa};
;                             S01 = S01 * (f32x2){w_[0], w_[1]} + vv * (f32x2){k_[0], k_[1]};
;                             S23 = S23 * (f32x2){w_[2], w_[3]} + vv * (f32x2){k_[2], k_[3]};
;                             S01 = sv * (f32x2){b_[0], b_[1]} + S01;
;                             S23 = sv * (f32x2){b_[2], b_[3]} + S23;
;                             rp = r_;
;                             a_ = a_n; w_ = w_n; b_ = b_n; k_ = k_n; r_ = r_n;
;                         }
	v_pk_mul_f32 v[114:115], v[166:167], v[62:63]
	v_pk_mul_f32 v[116:117], v[166:167], v[58:59]
	v_pk_fma_f32 v[114:115], v[164:165], v[64:65], v[114:115]
	v_pk_fma_f32 v[116:117], v[164:165], v[60:61], v[116:117]
	v_add_f32_e32 v122, v114, v115
	v_pk_mul_f32 v[118:119], v[100:101], v[74:75] op_sel:[1,0]
	v_add_f32_e32 v204, v116, v117
	ds_read_b128 v[54:57], v124 offset:22016
	ds_read_b128 v[46:49], v124 offset:13824
	ds_read_b128 v[50:53], v124 offset:38400
	ds_read_b128 v[58:61], v124 offset:5632
	ds_read_b128 v[42:45], v124 offset:30208
	v_add_f32_dpp v122, v122, v122 quad_perm:[1,0,3,2] row_mask:0xf bank_mask:0xf bound_ctrl:1
	v_pk_mul_f32 v[120:121], v[100:101], v[76:77] op_sel:[1,0]
	v_add_f32_dpp v221, v225, v225 row_half_mirror row_mask:0xf bank_mask:0xa bound_ctrl:1
	v_add_f32_dpp v122, v122, v122 quad_perm:[2,3,0,1] row_mask:0xf bank_mask:0xf bound_ctrl:1
	v_pk_fma_f32 v[166:167], v[166:167], v[66:67], v[118:119]
	v_add_f32_dpp v222, v226, v226 row_half_mirror row_mask:0xf bank_mask:0xa bound_ctrl:1
	v_add_f32_dpp v122, v122, v122 row_half_mirror row_mask:0xf bank_mask:0xf bound_ctrl:1
	v_pk_fma_f32 v[164:165], v[164:165], v[68:69], v[120:121]
	v_add_f32_dpp v223, v227, v227 row_half_mirror row_mask:0xf bank_mask:0xa bound_ctrl:1
	v_add_f32_dpp v122, v122, v122 row_mirror row_mask:0xf bank_mask:0xf bound_ctrl:1
	v_add_f32_dpp v220, v220, v220 quad_perm:[1,0,3,2] row_mask:0xf bank_mask:0xf bound_ctrl:1
	v_add_f32_dpp v221, v221, v221 quad_perm:[1,0,3,2] row_mask:0xf bank_mask:0xf bound_ctrl:1
	v_pk_fma_f32 v[166:167], v[70:71], v[122:123], v[166:167] op_sel_hi:[1,0,1]
	v_pk_fma_f32 v[164:165], v[72:73], v[122:123], v[164:165] op_sel_hi:[1,0,1]
	v_add_f32_dpp v222, v222, v222 quad_perm:[1,0,3,2] row_mask:0xf bank_mask:0xf bound_ctrl:1
	v_add_f32_dpp v223, v223, v223 quad_perm:[1,0,3,2] row_mask:0xf bank_mask:0xf bound_ctrl:1
	s_waitcnt lgkmcnt(11)
	v_pk_mul_f32 v[114:115], v[166:167], v[2:3]
	v_pk_mul_f32 v[116:117], v[166:167], v[78:79]
	v_pk_fma_f32 v[114:115], v[164:165], v[4:5], v[114:115]
	v_pk_fma_f32 v[116:117], v[164:165], v[80:81], v[116:117]
	v_add_f32_e32 v122, v114, v115
	s_waitcnt lgkmcnt(10)
	v_pk_mul_f32 v[118:119], v[102:103], v[14:15] op_sel_hi:[0,1]
	v_add_f32_e32 v205, v116, v117
	ds_read_b128 v[74:77], v124 offset:22272
	ds_read_b128 v[66:69], v124 offset:14080
	ds_read_b128 v[70:73], v124 offset:38656
	ds_read_b128 v[78:81], v124 offset:5888
	ds_read_b128 v[62:65], v124 offset:30464
	v_add_f32_dpp v122, v122, v122 quad_perm:[1,0,3,2] row_mask:0xf bank_mask:0xf bound_ctrl:1
	v_pk_mul_f32 v[120:121], v[102:103], v[16:17] op_sel_hi:[0,1]
	v_add_f32_dpp v220, v220, v220 quad_perm:[2,3,0,1] row_mask:0xf bank_mask:0xf bound_ctrl:1
	v_add_f32_dpp v122, v122, v122 quad_perm:[2,3,0,1] row_mask:0xf bank_mask:0xf bound_ctrl:1
	v_pk_fma_f32 v[166:167], v[166:167], v[6:7], v[118:119]
	v_add_f32_dpp v221, v221, v221 quad_perm:[2,3,0,1] row_mask:0xf bank_mask:0xf bound_ctrl:1
	v_add_f32_dpp v122, v122, v122 row_half_mirror row_mask:0xf bank_mask:0xf bound_ctrl:1
	v_pk_fma_f32 v[164:165], v[164:165], v[8:9], v[120:121]
	v_add_f32_dpp v222, v222, v222 quad_perm:[2,3,0,1] row_mask:0xf bank_mask:0xf bound_ctrl:1
	v_add_f32_dpp v122, v122, v122 row_mirror row_mask:0xf bank_mask:0xf bound_ctrl:1
	v_add_f32_dpp v223, v223, v223 quad_perm:[2,3,0,1] row_mask:0xf bank_mask:0xf bound_ctrl:1
	v_cndmask_b32_e64 v202, v220, v221, s[34:35]
	v_pk_fma_f32 v[166:167], v[10:11], v[122:123], v[166:167] op_sel_hi:[1,0,1]
	v_pk_fma_f32 v[164:165], v[12:13], v[122:123], v[164:165] op_sel_hi:[1,0,1]
	v_cndmask_b32_e64 v202, v202, v222, s[56:57]
	v_cndmask_b32_e64 v202, v202, v223, s[98:99]
	s_waitcnt lgkmcnt(10)
	v_pk_mul_f32 v[114:115], v[166:167], v[22:23]
	v_pk_mul_f32 v[116:117], v[166:167], v[18:19]
	v_pk_fma_f32 v[114:115], v[164:165], v[24:25], v[114:115]
	v_pk_fma_f32 v[116:117], v[164:165], v[20:21], v[116:117]
	v_add_f32_e32 v122, v114, v115
	v_pk_mul_f32 v[118:119], v[102:103], v[34:35] op_sel:[1,0]
	v_add_f32_e32 v206, v116, v117
	ds_read_b128 v[14:17], v124 offset:22528
	ds_read_b128 v[6:9], v124 offset:14336
	ds_read_b128 v[10:13], v124 offset:38912
	ds_read_b128 v[18:21], v124 offset:6144
	ds_read_b128 v[2:5], v124 offset:30720
	ds_read_b128 v[106:109], v125 offset:41056
	v_add_f32_dpp v122, v122, v122 quad_perm:[1,0,3,2] row_mask:0xf bank_mask:0xf bound_ctrl:1
	v_pk_mul_f32 v[120:121], v[102:103], v[36:37] op_sel:[1,0]
	v_cvt_f16_f32_e32 v203, v202
	v_add_f32_dpp v122, v122, v122 quad_perm:[2,3,0,1] row_mask:0xf bank_mask:0xf bound_ctrl:1
	v_pk_fma_f32 v[166:167], v[166:167], v[26:27], v[118:119]
	global_store_short v[126:127], v203, off
	v_add_f32_dpp v122, v122, v122 row_half_mirror row_mask:0xf bank_mask:0xf bound_ctrl:1
	v_pk_fma_f32 v[164:165], v[164:165], v[28:29], v[120:121]
	v_lshl_add_u64 v[126:127], v[126:127], 0, s[100:101]
	v_add_f32_dpp v122, v122, v122 row_mirror row_mask:0xf bank_mask:0xf bound_ctrl:1
	s_nop 0
	v_pk_fma_f32 v[166:167], v[30:31], v[122:123], v[166:167] op_sel_hi:[1,0,1]
	v_pk_fma_f32 v[164:165], v[32:33], v[122:123], v[164:165] op_sel_hi:[1,0,1]
	s_waitcnt lgkmcnt(11)
; #define LAS __attribute__((address_space(3)))
; template <int CTRL> __device__ __forceinline__ float dpp_f(float x) { return __int_as_float(__builtin_amdgcn_update_dpp(0, __float_as_int(x), CTRL, 0xf, 0xf, false)); }
; __device__ __forceinline__ void phase_scan(const Params& p, LAS unsigned char* lds) {
;     ...
;                         for (int u16 = 0; u16 < 16; ++u16) {
;                             const int s = 16 * hb + u16;
;                             const int sn = (s + 1) & 31;
;                             const f32x4 a_n = *(const LAS f32x4*)(sA + sn * 64), w_n = *(const LAS f32x4*)(sW + sn * 64), b_n = *(const LAS f32x4*)(sB + sn * 64);
;                             const f32x4 k_n = *(const LAS f32x4*)(sK + sn * 64), r_n = *(const LAS f32x4*)(sR + sn * 64);
;                             const float v = vq[u16 >> 2][u16 & 3];
;                             const f32x2 vv = {v, v};
;                             f32x2 pp = S01 * (f32x2){a_[0], a_[1]}; pp = S23 * (f32x2){a_[2], a_[3]} + pp;
;                             f32x2 yy = S01 * (f32x2){rp[0], rp[1]}; yy = S23 * (f32x2){rp[2], rp[3]} + yy;
;                             float sa = pp[0] + pp[1], y = yy[0] + yy[1];
;                             sa += dpp_f<0xB1>(sa); y += dpp_f<0xB1>(y);
;                             sa += dpp_f<0x4E>(sa); y += dpp_f<0x4E>(y);
;                             sa += dpp_f<0x141>(sa); y += dpp_f<0x141>(y);
;                             sa += dpp_f<0x140>(sa); y += dpp_f<0x140>(y);
;                             sY[((s - 1) & 31) * 16 + srow] = y;
;                             const f32x2 sv = {sa, sa};
;                             S01 = S01 * (f32x2){w_[0], w_[1]} + vv * (f32x2){k_[0], k_[1]};
;                             S23 = S23 * (f32x2){w_[2], w_[3]} + vv * (f32x2){k_[2], k_[3]};
;                             S01 = sv * (f32x2){b_[0], b_[1]} + S01;
;                             S23 = sv * (f32x2){b_[2], b_[3]} + S23;
;                             rp = r_;
;                             a_ = a_n; w_ = w_n; b_ = b_n; k_ = k_n; r_ = r_n;
;                         }
	v_pk_mul_f32 v[114:115], v[166:167], v[42:43]
	v_pk_mul_f32 v[116:117], v[166:167], v[38:39]
	v_pk_fma_f32 v[114:115], v[164:165], v[44:45], v[114:115]
	v_pk_fma_f32 v[116:117], v[164:165], v[40:41], v[116:117]
	v_add_f32_e32 v122, v114, v115
	v_pk_mul_f32 v[118:119], v[104:105], v[54:55] op_sel_hi:[0,1]
	v_add_f32_e32 v207, v116, v117
	ds_read_b128 v[34:37], v124 offset:22784
	ds_read_b128 v[26:29], v124 offset:14592
	ds_read_b128 v[30:33], v124 offset:39168
	ds_read_b128 v[38:41], v124 offset:6400
	ds_read_b128 v[22:25], v124 offset:30976
	v_add_f32_dpp v122, v122, v122 quad_perm:[1,0,3,2] row_mask:0xf bank_mask:0xf bound_ctrl:1
	v_pk_mul_f32 v[120:121], v[104:105], v[56:57] op_sel_hi:[0,1]
	s_nop 0
	v_add_f32_dpp v122, v122, v122 quad_perm:[2,3,0,1] row_mask:0xf bank_mask:0xf bound_ctrl:1
	v_pk_fma_f32 v[166:167], v[166:167], v[46:47], v[118:119]
	s_nop 0
	v_add_f32_dpp v122, v122, v122 row_half_mirror row_mask:0xf bank_mask:0xf bound_ctrl:1
	v_pk_fma_f32 v[164:165], v[164:165], v[48:49], v[120:121]
	s_nop 0
	v_add_f32_dpp v122, v122, v122 row_mirror row_mask:0xf bank_mask:0xf bound_ctrl:1
	s_nop 0
	v_pk_fma_f32 v[166:167], v[50:51], v[122:123], v[166:167] op_sel_hi:[1,0,1]
	v_pk_fma_f32 v[164:165], v[52:53], v[122:123], v[164:165] op_sel_hi:[1,0,1]
	s_waitcnt lgkmcnt(11)
	v_pk_mul_f32 v[114:115], v[166:167], v[62:63]
	v_pk_mul_f32 v[116:117], v[166:167], v[58:59]
	v_pk_fma_f32 v[114:115], v[164:165], v[64:65], v[114:115]
	v_pk_fma_f32 v[116:117], v[164:165], v[60:61], v[116:117]
	v_add_f32_e32 v122, v114, v115
	v_pk_mul_f32 v[118:119], v[104:105], v[74:75] op_sel:[1,0]
	v_add_f32_e32 v208, v116, v117
	ds_read_b128 v[54:57], v124 offset:23040
	ds_read_b128 v[46:49], v124 offset:14848
	ds_read_b128 v[50:53], v124 offset:39424
	ds_read_b128 v[58:61], v124 offset:6656
	ds_read_b128 v[42:45], v124 offset:31232
	v_add_f32_dpp v122, v122, v122 quad_perm:[1,0,3,2] row_mask:0xf bank_mask:0xf bound_ctrl:1
	v_pk_mul_f32 v[120:121], v[104:105], v[76:77] op_sel:[1,0]
	s_nop 0
	v_add_f32_dpp v122, v122, v122 quad_perm:[2,3,0,1] row_mask:0xf bank_mask:0xf bound_ctrl:1
	v_pk_fma_f32 v[166:167], v[166:167], v[66:67], v[118:119]
	s_nop 0
	v_add_f32_dpp v122, v122, v122 row_half_mirror row_mask:0xf bank_mask:0xf bound_ctrl:1
	v_pk_fma_f32 v[164:165], v[164:165], v[68:69], v[120:121]
	s_nop 0
	v_add_f32_dpp v122, v122, v122 row_mirror row_mask:0xf bank_mask:0xf bound_ctrl:1
	s_nop 0
	v_pk_fma_f32 v[166:167], v[70:71], v[122:123], v[166:167] op_sel_hi:[1,0,1]
	v_pk_fma_f32 v[164:165], v[72:73], v[122:123], v[164:165] op_sel_hi:[1,0,1]
	s_waitcnt lgkmcnt(11)
	v_pk_mul_f32 v[114:115], v[166:167], v[2:3]
	v_pk_mul_f32 v[116:117], v[166:167], v[78:79]
	v_pk_fma_f32 v[114:115], v[164:165], v[4:5], v[114:115]
	v_pk_fma_f32 v[116:117], v[164:165], v[80:81], v[116:117]
	v_add_f32_e32 v122, v114, v115
	s_waitcnt lgkmcnt(10)
	v_pk_mul_f32 v[118:119], v[106:107], v[14:15] op_sel_hi:[0,1]
	v_add_f32_e32 v209, v116, v117
	ds_read_b128 v[74:77], v124 offset:23296
	ds_read_b128 v[66:69], v124 offset:15104
	ds_read_b128 v[70:73], v124 offset:39680
	ds_read_b128 v[78:81], v124 offset:6912
	ds_read_b128 v[62:65], v124 offset:31488
	v_add_f32_dpp v122, v122, v122 quad_perm:[1,0,3,2] row_mask:0xf bank_mask:0xf bound_ctrl:1
	v_pk_mul_f32 v[120:121], v[106:107], v[16:17] op_sel_hi:[0,1]
	s_nop 0
	v_add_f32_dpp v122, v122, v122 quad_perm:[2,3,0,1] row_mask:0xf bank_mask:0xf bound_ctrl:1
	v_pk_fma_f32 v[166:167], v[166:167], v[6:7], v[118:119]
	s_nop 0
	v_add_f32_dpp v122, v122, v122 row_half_mirror row_mask:0xf bank_mask:0xf bound_ctrl:1
	v_pk_fma_f32 v[164:165], v[164:165], v[8:9], v[120:121]
	s_nop 0
	v_add_f32_dpp v122, v122, v122 row_mirror row_mask:0xf bank_mask:0xf bound_ctrl:1
	s_nop 0
	v_pk_fma_f32 v[166:167], v[10:11], v[122:123], v[166:167] op_sel_hi:[1,0,1]
	v_pk_fma_f32 v[164:165], v[12:13], v[122:123], v[164:165] op_sel_hi:[1,0,1]
	s_waitcnt lgkmcnt(10)
	v_pk_mul_f32 v[114:115], v[166:167], v[22:23]
	v_pk_mul_f32 v[116:117], v[166:167], v[18:19]
	v_pk_fma_f32 v[114:115], v[164:165], v[24:25], v[114:115]
	v_pk_fma_f32 v[116:117], v[164:165], v[20:21], v[116:117]
	v_add_f32_e32 v122, v114, v115
	v_pk_mul_f32 v[118:119], v[106:107], v[34:35] op_sel:[1,0]
	v_add_f32_e32 v210, v116, v117
	ds_read_b128 v[14:17], v124 offset:23552
	ds_read_b128 v[6:9], v124 offset:15360
	ds_read_b128 v[10:13], v124 offset:39936
	ds_read_b128 v[18:21], v124 offset:7168
	ds_read_b128 v[2:5], v124 offset:31744
	ds_read_b128 v[110:113], v125 offset:41072
	v_add_f32_dpp v122, v122, v122 quad_perm:[1,0,3,2] row_mask:0xf bank_mask:0xf bound_ctrl:1
	v_pk_mul_f32 v[120:121], v[106:107], v[36:37] op_sel:[1,0]
	s_nop 0
	v_add_f32_dpp v122, v122, v122 quad_perm:[2,3,0,1] row_mask:0xf bank_mask:0xf bound_ctrl:1
	v_pk_fma_f32 v[166:167], v[166:167], v[26:27], v[118:119]
	s_nop 0
	v_add_f32_dpp v122, v122, v122 row_half_mirror row_mask:0xf bank_mask:0xf bound_ctrl:1
	v_pk_fma_f32 v[164:165], v[164:165], v[28:29], v[120:121]
	s_nop 0
	v_add_f32_dpp v122, v122, v122 row_mirror row_mask:0xf bank_mask:0xf bound_ctrl:1
	s_nop 0
	v_pk_fma_f32 v[166:167], v[30:31], v[122:123], v[166:167] op_sel_hi:[1,0,1]
	v_pk_fma_f32 v[164:165], v[32:33], v[122:123], v[164:165] op_sel_hi:[1,0,1]
	s_waitcnt lgkmcnt(11)
; #define LAS __attribute__((address_space(3)))
; template <int CTRL> __device__ __forceinline__ float dpp_f(float x) { return __int_as_float(__builtin_amdgcn_update_dpp(0, __float_as_int(x), CTRL, 0xf, 0xf, false)); }
; #define LDS_BAR() do { asm volatile("s_waitcnt lgkmcnt(0)" ::: "memory"); __builtin_amdgcn_s_barrier(); asm volatile("" ::: "memory"); } while (0)
; __device__ __forceinline__ void phase_scan(const Params& p, LAS unsigned char* lds) {
;     ...
;                         for (int u16 = 0; u16 < 16; ++u16) {
;                             const int s = 16 * hb + u16;
;                             const int sn = (s + 1) & 31;
;                             const f32x4 a_n = *(const LAS f32x4*)(sA + sn * 64), w_n = *(const LAS f32x4*)(sW + sn * 64), b_n = *(const LAS f32x4*)(sB + sn * 64);
;                             const f32x4 k_n = *(const LAS f32x4*)(sK + sn * 64), r_n = *(const LAS f32x4*)(sR + sn * 64);
;                             const float v = vq[u16 >> 2][u16 & 3];
;                             const f32x2 vv = {v, v};
;                             f32x2 pp = S01 * (f32x2){a_[0], a_[1]}; pp = S23 * (f32x2){a_[2], a_[3]} + pp;
;                             f32x2 yy = S01 * (f32x2){rp[0], rp[1]}; yy = S23 * (f32x2){rp[2], rp[3]} + yy;
;                             float sa = pp[0] + pp[1], y = yy[0] + yy[1];
;                             sa += dpp_f<0xB1>(sa); y += dpp_f<0xB1>(y);
;                             sa += dpp_f<0x4E>(sa); y += dpp_f<0x4E>(y);
;                             sa += dpp_f<0x141>(sa); y += dpp_f<0x141>(y);
;                             sa += dpp_f<0x140>(sa); y += dpp_f<0x140>(y);
;                             sY[((s - 1) & 31) * 16 + srow] = y;
;                             const f32x2 sv = {sa, sa};
;                             S01 = S01 * (f32x2){w_[0], w_[1]} + vv * (f32x2){k_[0], k_[1]};
;                             S23 = S23 * (f32x2){w_[2], w_[3]} + vv * (f32x2){k_[2], k_[3]};
;                             S01 = sv * (f32x2){b_[0], b_[1]} + S01;
;                             S23 = sv * (f32x2){b_[2], b_[3]} + S23;
;                             rp = r_;
;                             a_ = a_n; w_ = w_n; b_ = b_n; k_ = k_n; r_ = r_n;
;                         }
;     ...
;             LDS_BAR();
	v_pk_mul_f32 v[114:115], v[166:167], v[42:43]
	v_pk_mul_f32 v[116:117], v[166:167], v[38:39]
	v_pk_fma_f32 v[114:115], v[164:165], v[44:45], v[114:115]
	v_pk_fma_f32 v[116:117], v[164:165], v[40:41], v[116:117]
	v_add_f32_e32 v122, v114, v115
	v_pk_mul_f32 v[118:119], v[108:109], v[54:55] op_sel_hi:[0,1]
	v_add_f32_e32 v211, v116, v117
	ds_read_b128 v[34:37], v124 offset:23808
	ds_read_b128 v[26:29], v124 offset:15616
	ds_read_b128 v[30:33], v124 offset:40192
	ds_read_b128 v[38:41], v124 offset:7424
	ds_read_b128 v[22:25], v124 offset:32000
	v_add_f32_dpp v122, v122, v122 quad_perm:[1,0,3,2] row_mask:0xf bank_mask:0xf bound_ctrl:1
	v_pk_mul_f32 v[120:121], v[108:109], v[56:57] op_sel_hi:[0,1]
	s_nop 0
	v_add_f32_dpp v122, v122, v122 quad_perm:[2,3,0,1] row_mask:0xf bank_mask:0xf bound_ctrl:1
	v_pk_fma_f32 v[166:167], v[166:167], v[46:47], v[118:119]
	s_nop 0
	v_add_f32_dpp v122, v122, v122 row_half_mirror row_mask:0xf bank_mask:0xf bound_ctrl:1
	v_pk_fma_f32 v[164:165], v[164:165], v[48:49], v[120:121]
	s_nop 0
	v_add_f32_dpp v122, v122, v122 row_mirror row_mask:0xf bank_mask:0xf bound_ctrl:1
	s_nop 0
	v_pk_fma_f32 v[166:167], v[50:51], v[122:123], v[166:167] op_sel_hi:[1,0,1]
	v_pk_fma_f32 v[164:165], v[52:53], v[122:123], v[164:165] op_sel_hi:[1,0,1]
	s_waitcnt lgkmcnt(11)
	v_pk_mul_f32 v[114:115], v[166:167], v[62:63]
	v_pk_mul_f32 v[116:117], v[166:167], v[58:59]
	v_pk_fma_f32 v[114:115], v[164:165], v[64:65], v[114:115]
	v_pk_fma_f32 v[116:117], v[164:165], v[60:61], v[116:117]
	v_add_f32_e32 v122, v114, v115
	v_pk_mul_f32 v[118:119], v[108:109], v[74:75] op_sel:[1,0]
	v_add_f32_e32 v212, v116, v117
	ds_read_b128 v[54:57], v124 offset:24064
	ds_read_b128 v[46:49], v124 offset:15872
	ds_read_b128 v[50:53], v124 offset:40448
	ds_read_b128 v[58:61], v124 offset:7680
	ds_read_b128 v[42:45], v124 offset:32256
	v_add_f32_dpp v122, v122, v122 quad_perm:[1,0,3,2] row_mask:0xf bank_mask:0xf bound_ctrl:1
	v_pk_mul_f32 v[120:121], v[108:109], v[76:77] op_sel:[1,0]
	s_nop 0
	v_add_f32_dpp v122, v122, v122 quad_perm:[2,3,0,1] row_mask:0xf bank_mask:0xf bound_ctrl:1
	v_pk_fma_f32 v[166:167], v[166:167], v[66:67], v[118:119]
	s_nop 0
	v_add_f32_dpp v122, v122, v122 row_half_mirror row_mask:0xf bank_mask:0xf bound_ctrl:1
	v_pk_fma_f32 v[164:165], v[164:165], v[68:69], v[120:121]
	s_nop 0
	v_add_f32_dpp v122, v122, v122 row_mirror row_mask:0xf bank_mask:0xf bound_ctrl:1
	s_nop 0
	v_pk_fma_f32 v[166:167], v[70:71], v[122:123], v[166:167] op_sel_hi:[1,0,1]
	v_pk_fma_f32 v[164:165], v[72:73], v[122:123], v[164:165] op_sel_hi:[1,0,1]
	ds_read_b128 v[74:77], v124 offset:24320
	ds_read_b128 v[66:69], v124 offset:16128
	ds_read_b128 v[70:73], v124 offset:40704
	ds_read_b128 v[62:65], v124 offset:32512
	s_waitcnt lgkmcnt(15)
	v_pk_mul_f32 v[114:115], v[166:167], v[2:3]
	v_pk_mul_f32 v[116:117], v[166:167], v[78:79]
	v_pk_fma_f32 v[114:115], v[164:165], v[4:5], v[114:115]
	v_pk_fma_f32 v[116:117], v[164:165], v[80:81], v[116:117]
	ds_read_b128 v[78:81], v124 offset:7936
	v_add_f32_e32 v122, v114, v115
	s_waitcnt lgkmcnt(15)
	v_pk_mul_f32 v[118:119], v[110:111], v[14:15] op_sel_hi:[0,1]
	v_add_f32_e32 v213, v116, v117
	v_add_f32_dpp v122, v122, v122 quad_perm:[1,0,3,2] row_mask:0xf bank_mask:0xf bound_ctrl:1
	v_pk_mul_f32 v[120:121], v[110:111], v[16:17] op_sel_hi:[0,1]
	s_nop 0
	v_add_f32_dpp v122, v122, v122 quad_perm:[2,3,0,1] row_mask:0xf bank_mask:0xf bound_ctrl:1
	v_pk_fma_f32 v[166:167], v[166:167], v[6:7], v[118:119]
	s_nop 0
	v_add_f32_dpp v122, v122, v122 row_half_mirror row_mask:0xf bank_mask:0xf bound_ctrl:1
	v_pk_fma_f32 v[164:165], v[164:165], v[8:9], v[120:121]
	s_nop 0
	v_add_f32_dpp v122, v122, v122 row_mirror row_mask:0xf bank_mask:0xf bound_ctrl:1
	s_nop 0
	v_pk_fma_f32 v[166:167], v[10:11], v[122:123], v[166:167] op_sel_hi:[1,0,1]
	v_pk_fma_f32 v[164:165], v[12:13], v[122:123], v[164:165] op_sel_hi:[1,0,1]
	s_waitcnt lgkmcnt(0)
	s_barrier
	s_add_i32 s81, s81, 1
	s_addk_i32 s82, 0x200
	s_cmpk_eq_i32 s81, 0x100
	s_cbranch_scc0 .Lscan_trip
	s_branch .LBB0_620
